# GEMM1 tail fill: short blocks take up to 9 weight-transposes tiles instead of 10
# speedup vs baseline: 1.0026x; 1.0026x over previous
.LBB0_441:
	s_barrier
	s_and_saveexec_b64 s[2:3], vcc
	s_cbranch_execz .LBB0_447
	s_cmp_gt_u32 s10, 8
	v_mov_b32_e32 v136, 0x670
	s_cbranch_scc1 .LBB0_446
	s_mov_b64 s[18:19], exec
	v_mbcnt_lo_u32_b32 v136, s18, 0
	v_mbcnt_hi_u32_b32 v136, s19, v136
	v_cmp_eq_u32_e64 s[0:1], 0, v136
	s_and_saveexec_b64 s[4:5], s[0:1]
	s_cbranch_execz .LBB0_445
	s_bcnt1_i32_b64 s0, s[18:19]
	v_mov_b32_e32 v137, s0
	global_atomic_add v137, v135, v137, s[6:7] sc0
